# sc4 + P3 S stores sc1
# speedup vs baseline: 1.0189x; 1.0003x over previous
; __device__ __forceinline__ unsigned f2bf(float f) { unsigned u = __builtin_bit_cast(unsigned, f); return (u + 0x7fffu + ((u >> 16) & 1u)) >> 16; }
; __device__ __forceinline__ void h2_phase(const Ptrs& P, int G, int tid) {
;     ...
;         for (int nb = 0; nb < NCH; nb += UB) {
;             h16x2 l[UB]; f32x2 dd[UB];
; #pragma unroll
;             for (int q = 0; q < UB; ++q) { l[q] = *(const h16x2*)(P.L + (size_t)(nb + q) * SLAB + off); dd[q] = *(const f32x2*)(P.Dn + (size_t)((nb + q) * NH + h) * HD + 2 * d2); }
; #pragma unroll
;             for (int q = 0; q < UB; ++q) {
;                 *(unsigned*)(P.S + (size_t)(nb + q) * SLAB + off) = f2bf(s0) | (f2bf(s1) << 16);
;                 s0 = dd[q][0] * s0 + (float)l[q][0]; s1 = dd[q][1] * s1 + (float)l[q][1]; }
;         }
.Lp3_loop:
	s_waitcnt vmcnt(38)
	v_cvt_pk_bf16_f32 v8, v6, v7
	s_add_u32 s24, s20, 0x0
	s_addc_u32 s25, s21, 0
	global_store_dword v4, v8, s[24:25] sc1
	v_cvt_f32_f16_e32 v9, v32
	v_cvt_f32_f16_sdwa v10, v32 dst_sel:DWORD dst_unused:UNUSED_PAD src0_sel:WORD_1
	v_fma_f32 v6, v48, v6, v9
	v_fma_f32 v7, v49, v7, v10
	s_waitcnt vmcnt(37)
	v_cvt_pk_bf16_f32 v11, v6, v7
	s_add_u32 s24, s20, 0x80000
	s_addc_u32 s25, s21, 0
	global_store_dword v4, v11, s[24:25] sc1
	v_cvt_f32_f16_e32 v9, v33
	v_cvt_f32_f16_sdwa v10, v33 dst_sel:DWORD dst_unused:UNUSED_PAD src0_sel:WORD_1
	v_fma_f32 v6, v50, v6, v9
	v_fma_f32 v7, v51, v7, v10
	s_waitcnt vmcnt(36)
	v_cvt_pk_bf16_f32 v8, v6, v7
	s_add_u32 s24, s20, 0x100000
	s_addc_u32 s25, s21, 0
	global_store_dword v4, v8, s[24:25] sc1
	v_cvt_f32_f16_e32 v9, v34
	v_cvt_f32_f16_sdwa v10, v34 dst_sel:DWORD dst_unused:UNUSED_PAD src0_sel:WORD_1
	v_fma_f32 v6, v52, v6, v9
	v_fma_f32 v7, v53, v7, v10
	s_waitcnt vmcnt(35)
	v_cvt_pk_bf16_f32 v11, v6, v7
	s_add_u32 s24, s20, 0x180000
	s_addc_u32 s25, s21, 0
	global_store_dword v4, v11, s[24:25] sc1
	v_cvt_f32_f16_e32 v9, v35
	v_cvt_f32_f16_sdwa v10, v35 dst_sel:DWORD dst_unused:UNUSED_PAD src0_sel:WORD_1
	v_fma_f32 v6, v54, v6, v9
	v_fma_f32 v7, v55, v7, v10
	s_waitcnt vmcnt(34)
	v_cvt_pk_bf16_f32 v8, v6, v7
	s_add_u32 s24, s20, 0x200000
	s_addc_u32 s25, s21, 0
	global_store_dword v4, v8, s[24:25] sc1
	v_cvt_f32_f16_e32 v9, v36
	v_cvt_f32_f16_sdwa v10, v36 dst_sel:DWORD dst_unused:UNUSED_PAD src0_sel:WORD_1
	v_fma_f32 v6, v56, v6, v9
	v_fma_f32 v7, v57, v7, v10
	s_waitcnt vmcnt(33)
	v_cvt_pk_bf16_f32 v11, v6, v7
	s_add_u32 s24, s20, 0x280000
	s_addc_u32 s25, s21, 0
	global_store_dword v4, v11, s[24:25] sc1
	v_cvt_f32_f16_e32 v9, v37
	v_cvt_f32_f16_sdwa v10, v37 dst_sel:DWORD dst_unused:UNUSED_PAD src0_sel:WORD_1
	v_fma_f32 v6, v58, v6, v9
	v_fma_f32 v7, v59, v7, v10
	s_waitcnt vmcnt(32)
	v_cvt_pk_bf16_f32 v8, v6, v7
	s_add_u32 s24, s20, 0x300000
	s_addc_u32 s25, s21, 0
	global_store_dword v4, v8, s[24:25] sc1
	v_cvt_f32_f16_e32 v9, v38
	v_cvt_f32_f16_sdwa v10, v38 dst_sel:DWORD dst_unused:UNUSED_PAD src0_sel:WORD_1
	v_fma_f32 v6, v60, v6, v9
	v_fma_f32 v7, v61, v7, v10
	s_waitcnt vmcnt(31)
	v_cvt_pk_bf16_f32 v11, v6, v7
	s_add_u32 s24, s20, 0x380000
	s_addc_u32 s25, s21, 0
	global_store_dword v4, v11, s[24:25] sc1
	v_cvt_f32_f16_e32 v9, v39
	v_cvt_f32_f16_sdwa v10, v39 dst_sel:DWORD dst_unused:UNUSED_PAD src0_sel:WORD_1
	v_fma_f32 v6, v62, v6, v9
	v_fma_f32 v7, v63, v7, v10
	s_add_u32 s20, s20, 0x400000
	s_addc_u32 s21, s21, 0
	s_add_u32 s24, s18, 0x0
	s_addc_u32 s25, s19, 0
	global_load_dword v32, v4, s[24:25]
	s_add_u32 s24, s22, 0x0
	s_addc_u32 s25, s23, 0
	global_load_dwordx2 v[48:49], v0, s[24:25]
	s_add_u32 s24, s18, 0x80000
	s_addc_u32 s25, s19, 0
	global_load_dword v33, v4, s[24:25]
	s_add_u32 s24, s22, 0x2000
	s_addc_u32 s25, s23, 0
	global_load_dwordx2 v[50:51], v0, s[24:25]
	s_add_u32 s24, s18, 0x100000
	s_addc_u32 s25, s19, 0
	global_load_dword v34, v4, s[24:25]
	s_add_u32 s24, s22, 0x4000
	s_addc_u32 s25, s23, 0
	global_load_dwordx2 v[52:53], v0, s[24:25]
	s_add_u32 s24, s18, 0x180000
	s_addc_u32 s25, s19, 0
	global_load_dword v35, v4, s[24:25]
	s_add_u32 s24, s22, 0x6000
	s_addc_u32 s25, s23, 0
	global_load_dwordx2 v[54:55], v0, s[24:25]
	s_add_u32 s24, s18, 0x200000
	s_addc_u32 s25, s19, 0
	global_load_dword v36, v4, s[24:25]
	s_add_u32 s24, s22, 0x8000
	s_addc_u32 s25, s23, 0
	global_load_dwordx2 v[56:57], v0, s[24:25]
	s_add_u32 s24, s18, 0x280000
	s_addc_u32 s25, s19, 0
	global_load_dword v37, v4, s[24:25]
	s_add_u32 s24, s22, 0xa000
	s_addc_u32 s25, s23, 0
	global_load_dwordx2 v[58:59], v0, s[24:25]
	s_add_u32 s24, s18, 0x300000
	s_addc_u32 s25, s19, 0
	global_load_dword v38, v4, s[24:25]
	s_add_u32 s24, s22, 0xc000
	s_addc_u32 s25, s23, 0
	global_load_dwordx2 v[60:61], v0, s[24:25]
	s_add_u32 s24, s18, 0x380000
	s_addc_u32 s25, s19, 0
	global_load_dword v39, v4, s[24:25]
	s_add_u32 s24, s22, 0xe000
	s_addc_u32 s25, s23, 0
	global_load_dwordx2 v[62:63], v0, s[24:25]
	s_add_u32 s18, s18, 0x400000
	s_addc_u32 s19, s19, 0
	s_add_u32 s22, s22, 0x10000
	s_addc_u32 s23, s23, 0
	s_waitcnt vmcnt(38)
	v_cvt_pk_bf16_f32 v8, v6, v7
	s_add_u32 s24, s20, 0x0
	s_addc_u32 s25, s21, 0
	global_store_dword v4, v8, s[24:25] sc1
	v_cvt_f32_f16_e32 v9, v40
	v_cvt_f32_f16_sdwa v10, v40 dst_sel:DWORD dst_unused:UNUSED_PAD src0_sel:WORD_1
	v_fma_f32 v6, v64, v6, v9
	v_fma_f32 v7, v65, v7, v10
	s_waitcnt vmcnt(37)
	v_cvt_pk_bf16_f32 v11, v6, v7
	s_add_u32 s24, s20, 0x80000
	s_addc_u32 s25, s21, 0
	global_store_dword v4, v11, s[24:25] sc1
	v_cvt_f32_f16_e32 v9, v41
	v_cvt_f32_f16_sdwa v10, v41 dst_sel:DWORD dst_unused:UNUSED_PAD src0_sel:WORD_1
	v_fma_f32 v6, v66, v6, v9
	v_fma_f32 v7, v67, v7, v10
	s_waitcnt vmcnt(36)
	v_cvt_pk_bf16_f32 v8, v6, v7
	s_add_u32 s24, s20, 0x100000
	s_addc_u32 s25, s21, 0
	global_store_dword v4, v8, s[24:25] sc1
	v_cvt_f32_f16_e32 v9, v42
	v_cvt_f32_f16_sdwa v10, v42 dst_sel:DWORD dst_unused:UNUSED_PAD src0_sel:WORD_1
	v_fma_f32 v6, v68, v6, v9
	v_fma_f32 v7, v69, v7, v10
	s_waitcnt vmcnt(35)
	v_cvt_pk_bf16_f32 v11, v6, v7
	s_add_u32 s24, s20, 0x180000
	s_addc_u32 s25, s21, 0
	global_store_dword v4, v11, s[24:25] sc1
	v_cvt_f32_f16_e32 v9, v43
	v_cvt_f32_f16_sdwa v10, v43 dst_sel:DWORD dst_unused:UNUSED_PAD src0_sel:WORD_1
	v_fma_f32 v6, v70, v6, v9
	v_fma_f32 v7, v71, v7, v10
	s_waitcnt vmcnt(34)
	v_cvt_pk_bf16_f32 v8, v6, v7
	s_add_u32 s24, s20, 0x200000
	s_addc_u32 s25, s21, 0
	global_store_dword v4, v8, s[24:25] sc1
	v_cvt_f32_f16_e32 v9, v44
	v_cvt_f32_f16_sdwa v10, v44 dst_sel:DWORD dst_unused:UNUSED_PAD src0_sel:WORD_1
	v_fma_f32 v6, v72, v6, v9
	v_fma_f32 v7, v73, v7, v10
	s_waitcnt vmcnt(33)
; __device__ __forceinline__ unsigned f2bf(float f) { unsigned u = __builtin_bit_cast(unsigned, f); return (u + 0x7fffu + ((u >> 16) & 1u)) >> 16; }
; __device__ __forceinline__ void h2_phase(const Ptrs& P, int G, int tid) {
;     ...
;         for (int nb = 0; nb < NCH; nb += UB) {
;             h16x2 l[UB]; f32x2 dd[UB];
; #pragma unroll
;             for (int q = 0; q < UB; ++q) { l[q] = *(const h16x2*)(P.L + (size_t)(nb + q) * SLAB + off); dd[q] = *(const f32x2*)(P.Dn + (size_t)((nb + q) * NH + h) * HD + 2 * d2); }
; #pragma unroll
;             for (int q = 0; q < UB; ++q) {
;                 *(unsigned*)(P.S + (size_t)(nb + q) * SLAB + off) = f2bf(s0) | (f2bf(s1) << 16);
;                 s0 = dd[q][0] * s0 + (float)l[q][0]; s1 = dd[q][1] * s1 + (float)l[q][1]; }
;         }
	v_cvt_pk_bf16_f32 v11, v6, v7
	s_add_u32 s24, s20, 0x280000
	s_addc_u32 s25, s21, 0
	global_store_dword v4, v11, s[24:25] sc1
	v_cvt_f32_f16_e32 v9, v45
	v_cvt_f32_f16_sdwa v10, v45 dst_sel:DWORD dst_unused:UNUSED_PAD src0_sel:WORD_1
	v_fma_f32 v6, v74, v6, v9
	v_fma_f32 v7, v75, v7, v10
	s_waitcnt vmcnt(32)
	v_cvt_pk_bf16_f32 v8, v6, v7
	s_add_u32 s24, s20, 0x300000
	s_addc_u32 s25, s21, 0
	global_store_dword v4, v8, s[24:25] sc1
	v_cvt_f32_f16_e32 v9, v46
	v_cvt_f32_f16_sdwa v10, v46 dst_sel:DWORD dst_unused:UNUSED_PAD src0_sel:WORD_1
	v_fma_f32 v6, v76, v6, v9
	v_fma_f32 v7, v77, v7, v10
	s_waitcnt vmcnt(31)
	v_cvt_pk_bf16_f32 v11, v6, v7
	s_add_u32 s24, s20, 0x380000
	s_addc_u32 s25, s21, 0
	global_store_dword v4, v11, s[24:25] sc1
	v_cvt_f32_f16_e32 v9, v47
	v_cvt_f32_f16_sdwa v10, v47 dst_sel:DWORD dst_unused:UNUSED_PAD src0_sel:WORD_1
	v_fma_f32 v6, v78, v6, v9
	v_fma_f32 v7, v79, v7, v10
	s_add_u32 s20, s20, 0x400000
	s_addc_u32 s21, s21, 0
	s_add_u32 s24, s18, 0x0
	s_addc_u32 s25, s19, 0
	global_load_dword v40, v4, s[24:25]
	s_add_u32 s24, s22, 0x0
	s_addc_u32 s25, s23, 0
	global_load_dwordx2 v[64:65], v0, s[24:25]
	s_add_u32 s24, s18, 0x80000
	s_addc_u32 s25, s19, 0
	global_load_dword v41, v4, s[24:25]
	s_add_u32 s24, s22, 0x2000
	s_addc_u32 s25, s23, 0
	global_load_dwordx2 v[66:67], v0, s[24:25]
	s_add_u32 s24, s18, 0x100000
	s_addc_u32 s25, s19, 0
	global_load_dword v42, v4, s[24:25]
	s_add_u32 s24, s22, 0x4000
	s_addc_u32 s25, s23, 0
	global_load_dwordx2 v[68:69], v0, s[24:25]
	s_add_u32 s24, s18, 0x180000
	s_addc_u32 s25, s19, 0
	global_load_dword v43, v4, s[24:25]
	s_add_u32 s24, s22, 0x6000
	s_addc_u32 s25, s23, 0
	global_load_dwordx2 v[70:71], v0, s[24:25]
	s_add_u32 s24, s18, 0x200000
	s_addc_u32 s25, s19, 0
	global_load_dword v44, v4, s[24:25]
	s_add_u32 s24, s22, 0x8000
	s_addc_u32 s25, s23, 0
	global_load_dwordx2 v[72:73], v0, s[24:25]
	s_add_u32 s24, s18, 0x280000
	s_addc_u32 s25, s19, 0
	global_load_dword v45, v4, s[24:25]
	s_add_u32 s24, s22, 0xa000
	s_addc_u32 s25, s23, 0
	global_load_dwordx2 v[74:75], v0, s[24:25]
	s_add_u32 s24, s18, 0x300000
	s_addc_u32 s25, s19, 0
	global_load_dword v46, v4, s[24:25]
	s_add_u32 s24, s22, 0xc000
	s_addc_u32 s25, s23, 0
	global_load_dwordx2 v[76:77], v0, s[24:25]
	s_add_u32 s24, s18, 0x380000
	s_addc_u32 s25, s19, 0
	global_load_dword v47, v4, s[24:25]
	s_add_u32 s24, s22, 0xe000
	s_addc_u32 s25, s23, 0
	global_load_dwordx2 v[78:79], v0, s[24:25]
	s_add_u32 s18, s18, 0x400000
	s_addc_u32 s19, s19, 0
	s_add_u32 s22, s22, 0x10000
	s_addc_u32 s23, s23, 0
	s_sub_u32 s26, s26, 1
	s_cmp_lg_u32 s26, 0
	s_cbranch_scc1 .Lp3_loop
; __device__ __forceinline__ unsigned f2bf(float f) { unsigned u = __builtin_bit_cast(unsigned, f); return (u + 0x7fffu + ((u >> 16) & 1u)) >> 16; }
; __device__ __forceinline__ void h2_phase(const Ptrs& P, int G, int tid) {
;     ...
;     for (int idx = blockIdx.x * 512 + tid; idx < NH * HD * (HD / 2); idx += G * 512) {
;         const int d2 = idx & 63, e = (idx >> 6) & 127, h = idx >> 13;
;         const size_t off = ((size_t)h * HD + e) * HD + 2 * d2;
;         float s0 = 0.f, s1 = 0.f;
;         for (int nb = 0; nb < NCH; nb += UB) {
;             h16x2 l[UB]; f32x2 dd[UB];
; #pragma unroll
;             for (int q = 0; q < UB; ++q) { l[q] = *(const h16x2*)(P.L + (size_t)(nb + q) * SLAB + off); dd[q] = *(const f32x2*)(P.Dn + (size_t)((nb + q) * NH + h) * HD + 2 * d2); }
; #pragma unroll
;             for (int q = 0; q < UB; ++q) {
;                 *(unsigned*)(P.S + (size_t)(nb + q) * SLAB + off) = f2bf(s0) | (f2bf(s1) << 16);
;                 s0 = dd[q][0] * s0 + (float)l[q][0]; s1 = dd[q][1] * s1 + (float)l[q][1]; }
;         }
	s_waitcnt vmcnt(38)
	v_cvt_pk_bf16_f32 v8, v6, v7
	s_add_u32 s24, s20, 0x0
	s_addc_u32 s25, s21, 0
	global_store_dword v4, v8, s[24:25] sc1
	v_cvt_f32_f16_e32 v9, v32
	v_cvt_f32_f16_sdwa v10, v32 dst_sel:DWORD dst_unused:UNUSED_PAD src0_sel:WORD_1
	v_fma_f32 v6, v48, v6, v9
	v_fma_f32 v7, v49, v7, v10
	s_waitcnt vmcnt(37)
	v_cvt_pk_bf16_f32 v11, v6, v7
	s_add_u32 s24, s20, 0x80000
	s_addc_u32 s25, s21, 0
	global_store_dword v4, v11, s[24:25] sc1
	v_cvt_f32_f16_e32 v9, v33
	v_cvt_f32_f16_sdwa v10, v33 dst_sel:DWORD dst_unused:UNUSED_PAD src0_sel:WORD_1
	v_fma_f32 v6, v50, v6, v9
	v_fma_f32 v7, v51, v7, v10
	s_waitcnt vmcnt(36)
	v_cvt_pk_bf16_f32 v8, v6, v7
	s_add_u32 s24, s20, 0x100000
	s_addc_u32 s25, s21, 0
	global_store_dword v4, v8, s[24:25] sc1
	v_cvt_f32_f16_e32 v9, v34
	v_cvt_f32_f16_sdwa v10, v34 dst_sel:DWORD dst_unused:UNUSED_PAD src0_sel:WORD_1
	v_fma_f32 v6, v52, v6, v9
	v_fma_f32 v7, v53, v7, v10
	s_waitcnt vmcnt(35)
	v_cvt_pk_bf16_f32 v11, v6, v7
	s_add_u32 s24, s20, 0x180000
	s_addc_u32 s25, s21, 0
	global_store_dword v4, v11, s[24:25] sc1
	v_cvt_f32_f16_e32 v9, v35
	v_cvt_f32_f16_sdwa v10, v35 dst_sel:DWORD dst_unused:UNUSED_PAD src0_sel:WORD_1
	v_fma_f32 v6, v54, v6, v9
	v_fma_f32 v7, v55, v7, v10
	s_waitcnt vmcnt(34)
	v_cvt_pk_bf16_f32 v8, v6, v7
	s_add_u32 s24, s20, 0x200000
	s_addc_u32 s25, s21, 0
	global_store_dword v4, v8, s[24:25] sc1
	v_cvt_f32_f16_e32 v9, v36
	v_cvt_f32_f16_sdwa v10, v36 dst_sel:DWORD dst_unused:UNUSED_PAD src0_sel:WORD_1
	v_fma_f32 v6, v56, v6, v9
	v_fma_f32 v7, v57, v7, v10
	s_waitcnt vmcnt(33)
	v_cvt_pk_bf16_f32 v11, v6, v7
	s_add_u32 s24, s20, 0x280000
	s_addc_u32 s25, s21, 0
	global_store_dword v4, v11, s[24:25] sc1
	v_cvt_f32_f16_e32 v9, v37
	v_cvt_f32_f16_sdwa v10, v37 dst_sel:DWORD dst_unused:UNUSED_PAD src0_sel:WORD_1
	v_fma_f32 v6, v58, v6, v9
	v_fma_f32 v7, v59, v7, v10
	s_waitcnt vmcnt(32)
	v_cvt_pk_bf16_f32 v8, v6, v7
	s_add_u32 s24, s20, 0x300000
	s_addc_u32 s25, s21, 0
	global_store_dword v4, v8, s[24:25] sc1
	v_cvt_f32_f16_e32 v9, v38
	v_cvt_f32_f16_sdwa v10, v38 dst_sel:DWORD dst_unused:UNUSED_PAD src0_sel:WORD_1
	v_fma_f32 v6, v60, v6, v9
	v_fma_f32 v7, v61, v7, v10
	s_waitcnt vmcnt(31)
	v_cvt_pk_bf16_f32 v11, v6, v7
	s_add_u32 s24, s20, 0x380000
	s_addc_u32 s25, s21, 0
	global_store_dword v4, v11, s[24:25] sc1
	v_cvt_f32_f16_e32 v9, v39
	v_cvt_f32_f16_sdwa v10, v39 dst_sel:DWORD dst_unused:UNUSED_PAD src0_sel:WORD_1
	v_fma_f32 v6, v62, v6, v9
	v_fma_f32 v7, v63, v7, v10
	s_add_u32 s20, s20, 0x400000
	s_addc_u32 s21, s21, 0
	s_waitcnt vmcnt(8)
	v_cvt_pk_bf16_f32 v8, v6, v7
	s_add_u32 s24, s20, 0x0
	s_addc_u32 s25, s21, 0
	global_store_dword v4, v8, s[24:25] sc1
	v_cvt_f32_f16_e32 v9, v40
	v_cvt_f32_f16_sdwa v10, v40 dst_sel:DWORD dst_unused:UNUSED_PAD src0_sel:WORD_1
	v_fma_f32 v6, v64, v6, v9
	v_fma_f32 v7, v65, v7, v10
	v_cvt_pk_bf16_f32 v11, v6, v7
	s_add_u32 s24, s20, 0x80000
	s_addc_u32 s25, s21, 0
	global_store_dword v4, v11, s[24:25] sc1
	v_cvt_f32_f16_e32 v9, v41
	v_cvt_f32_f16_sdwa v10, v41 dst_sel:DWORD dst_unused:UNUSED_PAD src0_sel:WORD_1
	v_fma_f32 v6, v66, v6, v9
	v_fma_f32 v7, v67, v7, v10
	v_cvt_pk_bf16_f32 v8, v6, v7
	s_add_u32 s24, s20, 0x100000
	s_addc_u32 s25, s21, 0
	global_store_dword v4, v8, s[24:25] sc1
	v_cvt_f32_f16_e32 v9, v42
	v_cvt_f32_f16_sdwa v10, v42 dst_sel:DWORD dst_unused:UNUSED_PAD src0_sel:WORD_1
	v_fma_f32 v6, v68, v6, v9
	v_fma_f32 v7, v69, v7, v10
	v_cvt_pk_bf16_f32 v11, v6, v7
	s_add_u32 s24, s20, 0x180000
	s_addc_u32 s25, s21, 0
	global_store_dword v4, v11, s[24:25] sc1
	v_cvt_f32_f16_e32 v9, v43
	v_cvt_f32_f16_sdwa v10, v43 dst_sel:DWORD dst_unused:UNUSED_PAD src0_sel:WORD_1
	v_fma_f32 v6, v70, v6, v9
	v_fma_f32 v7, v71, v7, v10
	v_cvt_pk_bf16_f32 v8, v6, v7
	s_add_u32 s24, s20, 0x200000
	s_addc_u32 s25, s21, 0
	global_store_dword v4, v8, s[24:25] sc1
	v_cvt_f32_f16_e32 v9, v44
	v_cvt_f32_f16_sdwa v10, v44 dst_sel:DWORD dst_unused:UNUSED_PAD src0_sel:WORD_1
	v_fma_f32 v6, v72, v6, v9
	v_fma_f32 v7, v73, v7, v10
	v_cvt_pk_bf16_f32 v11, v6, v7
	s_add_u32 s24, s20, 0x280000
	s_addc_u32 s25, s21, 0
	global_store_dword v4, v11, s[24:25] sc1
	v_cvt_f32_f16_e32 v9, v45
	v_cvt_f32_f16_sdwa v10, v45 dst_sel:DWORD dst_unused:UNUSED_PAD src0_sel:WORD_1
	v_fma_f32 v6, v74, v6, v9
	v_fma_f32 v7, v75, v7, v10
	v_cvt_pk_bf16_f32 v8, v6, v7
	s_add_u32 s24, s20, 0x300000
	s_addc_u32 s25, s21, 0
	global_store_dword v4, v8, s[24:25] sc1
	v_cvt_f32_f16_e32 v9, v46
	v_cvt_f32_f16_sdwa v10, v46 dst_sel:DWORD dst_unused:UNUSED_PAD src0_sel:WORD_1
	v_fma_f32 v6, v76, v6, v9
	v_fma_f32 v7, v77, v7, v10
	v_cvt_pk_bf16_f32 v11, v6, v7
	s_add_u32 s24, s20, 0x380000
	s_addc_u32 s25, s21, 0
	global_store_dword v4, v11, s[24:25] sc1
	v_cvt_f32_f16_e32 v9, v47
	v_cvt_f32_f16_sdwa v10, v47 dst_sel:DWORD dst_unused:UNUSED_PAD src0_sel:WORD_1
	v_fma_f32 v6, v78, v6, v9
	v_fma_f32 v7, v79, v7, v10
	s_add_u32 s20, s20, 0x400000
	s_addc_u32 s21, s21, 0
	v_add_u32_e32 v28, s6, v28
	v_cmp_lt_i32_e32 vcc, s54, v28
	s_or_b64 s[16:17], vcc, s[16:17]
	v_add_u32_e32 v29, s7, v29
	s_andn2_b64 exec, exec, s[16:17]
	s_cbranch_execnz .LBB0_294
